# attention QK: K fragment reads issued 8 ahead of their MFMA (on top of stagger)
# baseline (speedup 1.0000x reference)
; #define LAS __attribute__((address_space(3)))
; __device__ __forceinline__ void attn_unit(int bh, int qb, const bf16_t* Q, const bf16_t* KN, const bf16_t* KPE, const bf16_t* VT, const float* COS, const float* SIN, bf16_t* O, LAS unsigned char* lds, int wv) {
;     ...
;             const LAS unsigned char* kb = lds + buf * AK_BYTES + r32 * AK_PITCH + hi * 16;
;             f32x16 s0, s1;
; #pragma unroll
;             for (int r = 0; r < 16; ++r) { s0[r] = 0.f; s1[r] = 0.f; }
; #pragma unroll
;             for (int d0 = 0; d0 < 12; ++d0) { const bf16x8 k0 = *(const LAS bf16x8*)(kb + d0 * 32), k1 = *(const LAS bf16x8*)(kb + 32 * AK_PITCH + d0 * 32);
;                 s0 = __builtin_amdgcn_mfma_f32_32x32x16_bf16(k0, qf[d0], s0, 0, 0, 0); s1 = __builtin_amdgcn_mfma_f32_32x32x16_bf16(k1, qf[d0], s1, 0, 0, 0); }
;             if (t >= NT - 4) {
;                 const int kv0 = 64 * t + 4 * hi;
; #pragma unroll
;                 for (int r = 0; r < 16; ++r) { const int kv = kv0 + (r & 3) + 8 * (r >> 2); if (kv > qrow) s0[r] = -1e30f; if (kv + 32 > qrow) s1[r] = -1e30f; }
;             }
.LBB0_652:
	s_mul_i32 s16, s27, 0x6400
	v_add_u32_e32 v0, s16, v191
	s_cmp_lt_u32 s26, s56
	ds_read_b128 v[196:199], v0
	ds_read_b128 v[200:203], v0 offset:12800
	ds_read_b128 v[204:207], v0 offset:32
	ds_read_b128 v[208:211], v0 offset:12832
	ds_read_b128 v[212:215], v0 offset:64
	ds_read_b128 v[216:219], v0 offset:12864
	ds_read_b128 v[220:223], v0 offset:96
	ds_read_b128 v[224:227], v0 offset:12896
	s_waitcnt lgkmcnt(7)
	v_mfma_f32_32x32x16_bf16 v[80:95], v[196:199], v[112:115], 0
	ds_read_b128 v[196:199], v0 offset:128
	s_waitcnt lgkmcnt(7)
	v_mfma_f32_32x32x16_bf16 v[96:111], v[200:203], v[112:115], 0
	ds_read_b128 v[200:203], v0 offset:12928
	s_waitcnt lgkmcnt(7)
	v_mfma_f32_32x32x16_bf16 v[80:95], v[204:207], v[116:119], v[80:95]
	ds_read_b128 v[204:207], v0 offset:160
	s_waitcnt lgkmcnt(7)
	v_mfma_f32_32x32x16_bf16 v[96:111], v[208:211], v[116:119], v[96:111]
	ds_read_b128 v[208:211], v0 offset:12960
	s_waitcnt lgkmcnt(7)
	v_mfma_f32_32x32x16_bf16 v[80:95], v[212:215], v[120:123], v[80:95]
	ds_read_b128 v[212:215], v0 offset:192
	s_waitcnt lgkmcnt(7)
	v_mfma_f32_32x32x16_bf16 v[96:111], v[216:219], v[120:123], v[96:111]
	ds_read_b128 v[216:219], v0 offset:12992
	s_waitcnt lgkmcnt(7)
	v_mfma_f32_32x32x16_bf16 v[80:95], v[220:223], v[124:127], v[80:95]
	ds_read_b128 v[220:223], v0 offset:224
	s_waitcnt lgkmcnt(7)
	v_mfma_f32_32x32x16_bf16 v[96:111], v[224:227], v[124:127], v[96:111]
	ds_read_b128 v[224:227], v0 offset:13024
	s_waitcnt lgkmcnt(7)
	v_mfma_f32_32x32x16_bf16 v[80:95], v[196:199], v[128:131], v[80:95]
	ds_read_b128 v[196:199], v0 offset:256
	s_waitcnt lgkmcnt(7)
	v_mfma_f32_32x32x16_bf16 v[96:111], v[200:203], v[128:131], v[96:111]
	ds_read_b128 v[200:203], v0 offset:13056
	s_waitcnt lgkmcnt(7)
	v_mfma_f32_32x32x16_bf16 v[80:95], v[204:207], v[132:135], v[80:95]
	ds_read_b128 v[204:207], v0 offset:288
	s_waitcnt lgkmcnt(7)
	v_mfma_f32_32x32x16_bf16 v[96:111], v[208:211], v[132:135], v[96:111]
	ds_read_b128 v[208:211], v0 offset:13088
	s_waitcnt lgkmcnt(7)
	v_mfma_f32_32x32x16_bf16 v[80:95], v[212:215], v[136:139], v[80:95]
	ds_read_b128 v[212:215], v0 offset:320
	s_waitcnt lgkmcnt(7)
	v_mfma_f32_32x32x16_bf16 v[96:111], v[216:219], v[136:139], v[96:111]
	ds_read_b128 v[216:219], v0 offset:13120
	s_waitcnt lgkmcnt(7)
	v_mfma_f32_32x32x16_bf16 v[80:95], v[220:223], v[140:143], v[80:95]
	ds_read_b128 v[220:223], v0 offset:352
	s_waitcnt lgkmcnt(7)
	v_mfma_f32_32x32x16_bf16 v[96:111], v[224:227], v[140:143], v[96:111]
	ds_read_b128 v[224:227], v0 offset:13152
	s_waitcnt lgkmcnt(7)
	v_mfma_f32_32x32x16_bf16 v[80:95], v[196:199], v[144:147], v[80:95]
	s_waitcnt lgkmcnt(6)
	v_mfma_f32_32x32x16_bf16 v[96:111], v[200:203], v[144:147], v[96:111]
	s_waitcnt lgkmcnt(5)
	v_mfma_f32_32x32x16_bf16 v[80:95], v[204:207], v[152:155], v[80:95]
	s_waitcnt lgkmcnt(4)
	v_mfma_f32_32x32x16_bf16 v[96:111], v[208:211], v[152:155], v[96:111]
	s_waitcnt lgkmcnt(3)
	v_mfma_f32_32x32x16_bf16 v[80:95], v[212:215], v[148:151], v[80:95]
	s_waitcnt lgkmcnt(2)
	v_mfma_f32_32x32x16_bf16 v[96:111], v[216:219], v[148:151], v[96:111]
	s_waitcnt lgkmcnt(1)
	v_mfma_f32_32x32x16_bf16 v[80:95], v[220:223], v[156:159], v[80:95]
	s_waitcnt lgkmcnt(0)
	v_mfma_f32_32x32x16_bf16 v[96:111], v[224:227], v[156:159], v[96:111]
	s_cbranch_scc1 .LBB0_654
	v_add_u32_e32 v0, s21, v192
	v_add_u32_e32 v2, 32, v0
	v_cmp_le_i32_e32 vcc, v2, v160
	v_add_u32_e32 v2, 33, v0
	s_nop 6
	v_cndmask_b32_e32 v96, v187, v96, vcc
	v_cmp_lt_i32_e32 vcc, v0, v160
	s_nop 1
	v_cndmask_b32_e32 v81, v187, v81, vcc
	v_cmp_le_i32_e32 vcc, v0, v160
	s_nop 1
	v_cndmask_b32_e32 v80, v187, v80, vcc
	v_cmp_le_i32_e32 vcc, v2, v160
	v_add_u32_e32 v2, 2, v0
	s_nop 0
	v_cndmask_b32_e32 v97, v187, v97, vcc
	v_cmp_le_i32_e32 vcc, v2, v160
	v_add_u32_e32 v2, 34, v0
	s_nop 0
	v_cndmask_b32_e32 v82, v187, v82, vcc
	v_cmp_le_i32_e32 vcc, v2, v160
	v_add_u32_e32 v2, 3, v0
	s_nop 0
	v_cndmask_b32_e32 v98, v187, v98, vcc
	v_cmp_le_i32_e32 vcc, v2, v160
	v_add_u32_e32 v2, 35, v0
	s_nop 0
	v_cndmask_b32_e32 v83, v187, v83, vcc
	v_cmp_le_i32_e32 vcc, v2, v160
	v_add_u32_e32 v2, 8, v0
	s_nop 0
	v_cndmask_b32_e32 v99, v187, v99, vcc
	v_cmp_le_i32_e32 vcc, v2, v160
	v_add_u32_e32 v2, 40, v0
	s_nop 0
	v_cndmask_b32_e32 v84, v187, v84, vcc
	v_cmp_le_i32_e32 vcc, v2, v160
	v_add_u32_e32 v2, 9, v0
	s_nop 0
	v_cndmask_b32_e32 v100, v187, v100, vcc
	v_cmp_le_i32_e32 vcc, v2, v160
	v_add_u32_e32 v2, 41, v0
	s_nop 0
	v_cndmask_b32_e32 v85, v187, v85, vcc
	v_cmp_le_i32_e32 vcc, v2, v160
	v_add_u32_e32 v2, 10, v0
	s_nop 0
	v_cndmask_b32_e32 v101, v187, v101, vcc
	v_cmp_le_i32_e32 vcc, v2, v160
	v_add_u32_e32 v2, 42, v0
	s_nop 0
	v_cndmask_b32_e32 v86, v187, v86, vcc
	v_cmp_le_i32_e32 vcc, v2, v160
	v_add_u32_e32 v2, 11, v0
	s_nop 0
	v_cndmask_b32_e32 v102, v187, v102, vcc
	v_cmp_le_i32_e32 vcc, v2, v160
	v_add_u32_e32 v2, 43, v0
	s_nop 0
	v_cndmask_b32_e32 v87, v187, v87, vcc
	v_cmp_le_i32_e32 vcc, v2, v160
	v_add_u32_e32 v2, 16, v0
	s_nop 0
	v_cndmask_b32_e32 v103, v187, v103, vcc
	v_cmp_le_i32_e32 vcc, v2, v160
	v_add_u32_e32 v2, 48, v0
	s_nop 0
	v_cndmask_b32_e32 v88, v187, v88, vcc
	v_cmp_le_i32_e32 vcc, v2, v160
	v_add_u32_e32 v2, 17, v0
	s_nop 0
	v_cndmask_b32_e32 v104, v187, v104, vcc
	v_cmp_le_i32_e32 vcc, v2, v160
	v_add_u32_e32 v2, 49, v0
	s_nop 0
	v_cndmask_b32_e32 v89, v187, v89, vcc
	v_cmp_le_i32_e32 vcc, v2, v160
	v_add_u32_e32 v2, 18, v0
	s_nop 0
	v_cndmask_b32_e32 v105, v187, v105, vcc
	v_cmp_le_i32_e32 vcc, v2, v160
	v_add_u32_e32 v2, 50, v0
	s_nop 0
	v_cndmask_b32_e32 v90, v187, v90, vcc
	v_cmp_le_i32_e32 vcc, v2, v160
	v_add_u32_e32 v2, 19, v0
	s_nop 0
	v_cndmask_b32_e32 v106, v187, v106, vcc
	v_cmp_le_i32_e32 vcc, v2, v160
	v_add_u32_e32 v2, 51, v0
	s_nop 0
	v_cndmask_b32_e32 v91, v187, v91, vcc
	v_cmp_le_i32_e32 vcc, v2, v160
	v_add_u32_e32 v2, 24, v0
	s_nop 0
	v_cndmask_b32_e32 v107, v187, v107, vcc
	v_cmp_le_i32_e32 vcc, v2, v160
	v_add_u32_e32 v2, 56, v0
	s_nop 0
	v_cndmask_b32_e32 v92, v187, v92, vcc
	v_cmp_le_i32_e32 vcc, v2, v160
	v_add_u32_e32 v2, 25, v0
	s_nop 0
	v_cndmask_b32_e32 v108, v187, v108, vcc
	v_cmp_le_i32_e32 vcc, v2, v160
	v_add_u32_e32 v2, 57, v0
	s_nop 0
	v_cndmask_b32_e32 v93, v187, v93, vcc
	v_cmp_le_i32_e32 vcc, v2, v160
	v_add_u32_e32 v2, 26, v0
	s_nop 0
	v_cndmask_b32_e32 v109, v187, v109, vcc
	v_cmp_le_i32_e32 vcc, v2, v160
	v_add_u32_e32 v2, 58, v0
	s_nop 0
	v_cndmask_b32_e32 v94, v187, v94, vcc
	v_cmp_le_i32_e32 vcc, v2, v160
	v_add_u32_e32 v2, 27, v0
	v_add_u32_e32 v0, 59, v0
	v_cndmask_b32_e32 v110, v187, v110, vcc
	v_cmp_le_i32_e32 vcc, v2, v160
	s_nop 1
	v_cndmask_b32_e32 v95, v187, v95, vcc
	v_cmp_le_i32_e32 vcc, v0, v160
	s_nop 1
	v_cndmask_b32_e32 v111, v187, v111, vcc
